# v41 plus: scan compute waves no longer stall on next-chunk operand register shuffles right after the first MFMA (copies sunk to chunk end)
# baseline (speedup 1.0000x reference)
; __device__ __forceinline__ void wkv_scan_mfma(const PT& a, int seq, LAS unsigned char* lds, unsigned long long& busy) {
;     ...
; #pragma unroll 1
;         for (int c = 0; c < NCH; c += 2) { S7_CITER(c, oA, oB); S7_CITER(c + 1, oB, oA); }
.LBB0_1212:
	s_mul_i32 s4, s1, 0xab
	s_bfe_u32 s5, s4, 0x70009
	s_addk_i32 s4, 0xab
	s_mul_i32 s5, s5, 3
	s_bfe_u32 s4, s4, 0x70009
	s_sub_i32 s5, s1, s5
	s_mul_i32 s4, s4, 3
	s_and_b32 s5, s5, 0xff
	s_sub_i32 s4, s1, s4
	s_mulk_i32 s5, 0x6100
	s_add_i32 s4, s4, 1
	v_add_u32_e32 v38, s5, v243
	ds_read_b128 v[110:113], v239
	ds_read_b128 v[118:121], v238
	ds_read_b128 v[98:101], v237
	ds_read_b128 v[102:105], v236
	ds_read_b128 v[34:37], v38 offset:448
	ds_read_b128 v[42:45], v38 offset:384
	ds_read_b128 v[46:49], v38 offset:320
	ds_read_b128 v[50:53], v38 offset:256
	s_and_b32 s4, s4, 0xff
	s_mulk_i32 s4, 0x6100
	s_add_i32 s4, s4, 0
	v_lshl_add_u32 v130, v234, 2, s4
	v_add3_u32 v106, s4, v235, v144
	v_add_u32_e32 v78, v130, v233
	v_lshl_add_u32 v38, s0, 2, v106
	s_waitcnt lgkmcnt(4)
	s_waitcnt lgkmcnt(0)
	s_waitcnt lgkmcnt(0)
	ds_read_b32 v250, v38 offset:5936
	ds_read_b32 v251, v38 offset:4384
	ds_read_b32 v224, v38 offset:2832
	ds_read_b32 v213, v38 offset:1280
	ds_read_b128 v[38:41], v78 offset:1216
	ds_read_b128 v[58:61], v78 offset:1152
	ds_read_b128 v[54:57], v78 offset:192
	ds_read_b128 v[62:65], v78 offset:128
	ds_read_b128 v[66:69], v78 offset:1088
	ds_read_b128 v[74:77], v78 offset:1024
	ds_read_b128 v[70:73], v78 offset:64
	ds_read_b128 v[78:81], v78
	ds_read2_b32 v[190:191], v106 offset0:224 offset1:240
	ds_read2_b32 v[184:185], v106 offset0:160 offset1:176
	ds_read2_b32 v[196:197], v106 offset0:192 offset1:208
	ds_read2_b32 v[186:187], v106 offset0:128 offset1:144
	v_add_u32_e32 v107, 0x800, v106
	ds_read2_b32 v[198:199], v107 offset0:100 offset1:116
	ds_read2_b32 v[188:189], v107 offset0:36 offset1:52
	ds_read2_b32 v[202:203], v107 offset0:68 offset1:84
	ds_read2_b32 v[192:193], v107 offset0:4 offset1:20
	v_add_u32_e32 v107, 0xc00, v106
	v_add_u32_e32 v106, 0x1400, v106
	ds_read2_b32 v[204:205], v107 offset0:232 offset1:248
	ds_read2_b32 v[194:195], v107 offset0:168 offset1:184
	ds_read2_b32 v[206:207], v107 offset0:200 offset1:216
	ds_read2_b32 v[200:201], v107 offset0:136 offset1:152
	ds_read2_b32 v[208:209], v106 offset0:108 offset1:124
	ds_read2_b32 v[180:181], v106 offset0:44 offset1:60
	ds_read2_b32 v[210:211], v106 offset0:76 offset1:92
	ds_read2_b32 v[182:183], v106 offset0:12 offset1:28
	v_mfma_f32_16x16x4_f32 v[106:109], v2, v94, 0
	s_cmpk_gt_u32 s1, 0x7d
	s_cselect_b64 s[4:5], -1, 0
	s_and_b64 vcc, exec, s[4:5]
	v_mfma_f32_16x16x4_f32 v[106:109], v3, v95, v[106:109]
	v_mfma_f32_16x16x4_f32 v[106:109], v4, v96, v[106:109]
	v_mfma_f32_16x16x4_f32 v[106:109], v5, v97, v[106:109]
	v_mfma_f32_16x16x4_f32 v[106:109], v6, v90, v[106:109]
	v_mfma_f32_16x16x4_f32 v[114:117], v10, v94, 0
	v_mfma_f32_16x16x4_f32 v[106:109], v7, v91, v[106:109]
	v_mfma_f32_16x16x4_f32 v[114:117], v11, v95, v[114:117]
	v_mfma_f32_16x16x4_f32 v[106:109], v8, v92, v[106:109]
	v_mfma_f32_16x16x4_f32 v[114:117], v12, v96, v[114:117]
	v_mfma_f32_16x16x4_f32 v[106:109], v9, v93, v[106:109]
	v_mfma_f32_16x16x4_f32 v[114:117], v13, v97, v[114:117]
	v_mfma_f32_16x16x4_f32 v[106:109], v18, v86, v[106:109]
	v_mfma_f32_16x16x4_f32 v[114:117], v14, v90, v[114:117]
	v_mfma_f32_16x16x4_f32 v[106:109], v19, v87, v[106:109]
	v_mfma_f32_16x16x4_f32 v[114:117], v15, v91, v[114:117]
	v_mfma_f32_16x16x4_f32 v[106:109], v20, v88, v[106:109]
	v_mfma_f32_16x16x4_f32 v[114:117], v16, v92, v[114:117]
	v_mfma_f32_16x16x4_f32 v[106:109], v21, v89, v[106:109]
	v_mfma_f32_16x16x4_f32 v[114:117], v17, v93, v[114:117]
	v_mfma_f32_16x16x4_f32 v[106:109], v22, v82, v[106:109]
	v_mfma_f32_16x16x4_f32 v[114:117], v26, v86, v[114:117]
	v_mfma_f32_16x16x4_f32 v[106:109], v23, v83, v[106:109]
	v_mfma_f32_16x16x4_f32 v[114:117], v27, v87, v[114:117]
	v_mfma_f32_16x16x4_f32 v[106:109], v24, v84, v[106:109]
	v_mfma_f32_16x16x4_f32 v[114:117], v28, v88, v[114:117]
	v_mfma_f32_16x16x4_f32 v[106:109], v25, v85, v[106:109]
	v_mfma_f32_16x16x4_f32 v[114:117], v29, v89, v[114:117]
	v_mfma_f32_16x16x4_f32 v[106:109], v102, v246, v[106:109]
	v_mfma_f32_16x16x4_f32 v[114:117], v30, v82, v[114:117]
	v_mfma_f32_16x16x4_f32 v[106:109], v103, v247, v[106:109]
	v_mfma_f32_16x16x4_f32 v[114:117], v31, v83, v[114:117]
	v_mfma_f32_16x16x4_f32 v[106:109], v104, v248, v[106:109]
	v_mfma_f32_16x16x4_f32 v[114:117], v32, v84, v[114:117]
	v_mfma_f32_16x16x4_f32 v[102:105], v105, v249, v[106:109]
	v_mfma_f32_16x16x4_f32 v[122:125], v33, v85, v[114:117]
	s_nop 8
	v_mfma_f32_16x16x4_f32 v[106:109], v98, v102, 0
	v_mfma_f32_16x16x4_f32 v[86:89], v152, v246, v[86:89]
	v_mfma_f32_16x16x4_f32 v[82:85], v153, v246, v[82:85]
	v_mfma_f32_16x16x4_f32 v[106:109], v99, v103, v[106:109]
	v_mfma_f32_16x16x4_f32 v[86:89], v160, v247, v[86:89]
	v_mfma_f32_16x16x4_f32 v[82:85], v161, v247, v[82:85]
	v_mfma_f32_16x16x4_f32 v[106:109], v100, v104, v[106:109]
	v_mfma_f32_16x16x4_f32 v[86:89], v170, v248, v[86:89]
	v_mfma_f32_16x16x4_f32 v[82:85], v171, v248, v[82:85]
	v_mfma_f32_16x16x4_f32 v[126:129], v101, v105, v[106:109]
	v_mfma_f32_16x16x4_f32 v[86:89], v178, v249, v[86:89]
	v_mfma_f32_16x16x4_f32 v[82:85], v179, v249, v[82:85]
	v_mfma_f32_16x16x4_f32 v[90:93], v149, v246, v[90:93]
	s_nop 6
	v_mfma_f32_16x16x4_f32 v[86:89], v150, v126, v[86:89]
; __device__ __forceinline__ void wkv_scan_mfma(const PT& a, int seq, LAS unsigned char* lds, unsigned long long& busy) {
;     ...
; #pragma unroll 1
;         for (int c = 0; c < NCH; c += 2) { S7_CITER(c, oA, oB); S7_CITER(c + 1, oB, oA); }
	v_mfma_f32_16x16x4_f32 v[82:85], v151, v126, v[82:85]
	v_mfma_f32_16x16x4_f32 v[90:93], v157, v247, v[90:93]
	v_mfma_f32_16x16x4_f32 v[86:89], v158, v127, v[86:89]
	v_mfma_f32_16x16x4_f32 v[82:85], v159, v127, v[82:85]
	v_mfma_f32_16x16x4_f32 v[94:97], v148, v246, v[94:97]
	v_mfma_f32_16x16x4_f32 v[90:93], v167, v248, v[90:93]
	v_mfma_f32_16x16x4_f32 v[86:89], v168, v128, v[86:89]
	v_mfma_f32_16x16x4_f32 v[82:85], v169, v128, v[82:85]
	v_mfma_f32_16x16x4_f32 v[94:97], v156, v247, v[94:97]
	v_mfma_f32_16x16x4_f32 v[90:93], v175, v249, v[90:93]
	v_mfma_f32_16x16x4_f32 v[102:105], v176, v129, v[86:89]
	v_mfma_f32_16x16x4_f32 v[98:101], v177, v129, v[82:85]
	v_mfma_f32_16x16x4_f32 v[82:85], v118, v126, v[122:125]
	v_mfma_f32_16x16x4_f32 v[86:89], v110, v246, 0
	v_mfma_f32_16x16x4_f32 v[94:97], v166, v248, v[94:97]
	v_mfma_f32_16x16x4_f32 v[90:93], v147, v126, v[90:93]
	v_mfma_f32_16x16x4_f32 v[82:85], v119, v127, v[82:85]
	v_mfma_f32_16x16x4_f32 v[86:89], v111, v247, v[86:89]
	v_mfma_f32_16x16x4_f32 v[94:97], v174, v249, v[94:97]
	v_mfma_f32_16x16x4_f32 v[90:93], v155, v127, v[90:93]
	v_mfma_f32_16x16x4_f32 v[82:85], v120, v128, v[82:85]
	v_mfma_f32_16x16x4_f32 v[86:89], v112, v248, v[86:89]
	v_mfma_f32_16x16x4_f32 v[94:97], v146, v126, v[94:97]
	v_mfma_f32_16x16x4_f32 v[90:93], v165, v128, v[90:93]
	v_mfma_f32_16x16x4_f32 v[82:85], v121, v129, v[82:85]
	v_mfma_f32_16x16x4_f32 v[86:89], v113, v249, v[86:89]
	v_mfma_f32_16x16x4_f32 v[94:97], v154, v127, v[94:97]
	s_nop 8
	v_add_f32_e32 v82, v82, v86
	v_add_u32_e32 v86, -1, v244
	v_add_f32_e32 v84, v84, v88
	v_mfma_f32_16x16x4_f32 v[106:109], v173, v129, v[90:93]
	v_cndmask_b32_e64 v90, v244, v245, s[8:9]
	v_add_u32_e32 v132, s6, v90
	v_lshlrev_b64 v[90:91], 12, v[132:133]
	v_lshl_add_u64 v[90:91], v[162:163], 0, v[90:91]
	global_store_dword v[90:91], v82, off
	v_add_u32_e32 v82, 1, v245
	v_cndmask_b32_e64 v82, v86, v82, s[8:9]
	v_add_u32_e32 v132, s6, v82
	v_add_f32_e32 v86, v83, v87
	v_lshlrev_b64 v[82:83], 12, v[132:133]
	v_mfma_f32_16x16x4_f32 v[94:97], v164, v128, v[94:97]
	v_lshl_add_u64 v[82:83], v[162:163], 0, v[82:83]
	global_store_dword v[82:83], v86, off
	v_add_u32_e32 v82, 2, v245
	v_add_u32_e32 v83, -2, v244
	v_cndmask_b32_e64 v82, v83, v82, s[8:9]
	v_add_u32_e32 v132, s6, v82
	v_lshlrev_b64 v[82:83], 12, v[132:133]
	v_lshl_add_u64 v[82:83], v[162:163], 0, v[82:83]
	global_store_dword v[82:83], v84, off
	v_add_u32_e32 v82, 3, v245
	v_add_u32_e32 v83, -3, v244
	v_cndmask_b32_e64 v82, v83, v82, s[8:9]
	v_mfma_f32_16x16x4_f32 v[114:117], v172, v129, v[94:97]
	v_add_u32_e32 v132, s6, v82
	v_lshlrev_b64 v[82:83], 12, v[132:133]
	v_add_f32_e32 v84, v85, v89
	v_lshl_add_u64 v[82:83], v[162:163], 0, v[82:83]
	global_store_dword v[82:83], v84, off
	s_waitcnt lgkmcnt(0)
	v_mov_b32_e32 v214, v191
	v_mov_b32_e32 v191, v192
	v_mov_b32_e32 v192, v201
	v_mov_b32_e32 v201, v210
	s_barrier
	ds_read_b128 v[110:113], v242
	ds_read_b128 v[118:121], v241
	ds_read_b128 v[122:125], v240
	ds_read_b128 v[126:129], v145
	ds_read_b128 v[82:85], v130 offset:448
	ds_read_b128 v[86:89], v130 offset:384
	ds_read_b128 v[90:93], v130 offset:320
	ds_read_b128 v[94:97], v130 offset:256
	s_waitcnt lgkmcnt(4)
	s_waitcnt lgkmcnt(0)
	v_mov_b32_e32 v132, v186
	v_mov_b32_e32 v186, v184
	v_mov_b32_e32 v184, v195
	v_mov_b32_e32 v195, v208
	s_waitcnt lgkmcnt(0)
	s_cbranch_vccnz .LBB0_1211
	s_add_i32 s6, s1, 2
	s_and_b32 s7, s6, 0xff
	s_mulk_i32 s7, 0xab
	s_bfe_u32 s7, s7, 0x70009
	s_mul_i32 s7, s7, 3
	s_sub_i32 s6, s6, s7
	s_and_b32 s6, s6, 0xff
	s_mulk_i32 s6, 0x6100
	s_add_i32 s6, s6, 0
	v_lshlrev_b32_e32 v2, 2, v234
	v_add3_u32 v130, s6, v235, v144
	v_add3_u32 v30, s6, v233, v2
	v_add_u32_e32 v134, 0x800, v130
	ds_read_b128 v[2:5], v30
	ds_read_b128 v[6:9], v30 offset:64
	ds_read_b128 v[10:13], v30 offset:1024
	ds_read_b128 v[14:17], v30 offset:1088
	ds_read_b128 v[18:21], v30 offset:128
	ds_read_b128 v[22:25], v30 offset:192
	ds_read_b128 v[26:29], v30 offset:1152
	ds_read_b128 v[30:33], v30 offset:1216
	ds_read2_b32 v[146:147], v130 offset0:128 offset1:144
	ds_read2_b32 v[148:149], v130 offset0:192 offset1:208
	ds_read2_b32 v[150:151], v130 offset0:160 offset1:176
	ds_read2_b32 v[152:153], v130 offset0:224 offset1:240
	ds_read2_b32 v[154:155], v134 offset0:4 offset1:20
	ds_read2_b32 v[156:157], v134 offset0:68 offset1:84
	ds_read2_b32 v[158:159], v134 offset0:36 offset1:52
	ds_read2_b32 v[160:161], v134 offset0:100 offset1:116
	v_add_u32_e32 v134, 0xc00, v130
	v_lshl_add_u32 v131, s0, 2, v130
	ds_read2_b32 v[164:165], v134 offset0:136 offset1:152
	ds_read2_b32 v[166:167], v134 offset0:200 offset1:216
	ds_read2_b32 v[168:169], v134 offset0:168 offset1:184
	ds_read2_b32 v[170:171], v134 offset0:232 offset1:248
	ds_read_b32 v246, v131 offset:1280
	ds_read_b32 v247, v131 offset:2832
	ds_read_b32 v248, v131 offset:4384
	ds_read_b32 v249, v131 offset:5936
	v_add_u32_e32 v130, 0x1400, v130
	ds_read2_b32 v[172:173], v130 offset0:12 offset1:28
	ds_read2_b32 v[174:175], v130 offset0:76 offset1:92
	ds_read2_b32 v[176:177], v130 offset0:44 offset1:60
	ds_read2_b32 v[178:179], v130 offset0:108 offset1:124
	v_readlane_b32 s6, v253, 48
	s_branch .LBB0_1211
